# diff attention: comp-1 waves (4-7) delayed by s_sleep 6 after the tile-pair barrier so the two waves of a SIMD leave lockstep (MFMA phases of one overlap softmax VALU of the other)
# baseline (speedup 1.0000x reference)
; #define LAS __attribute__((address_space(3)))
; __device__ __forceinline__ void df_attn_phase(int j, float lambda_init, LAS unsigned char* lds, unsigned* ctr) {
;     ...
;                 *(LAS u32x4*)(lds + kofs) = ka0; *(LAS u32x4*)(lds + kofs + 32 * AT_KPITCH) = ka1; *(LAS u32x4*)(lds + vofs) = va0; *(LAS u32x4*)(lds + vofs + 32 * 64) = va1;
;                 *(LAS u32x4*)(lds + AT_BUF + kofs) = kb0; *(LAS u32x4*)(lds + AT_BUF + kofs + 32 * AT_KPITCH) = kb1; *(LAS u32x4*)(lds + AT_BUF + vofs) = vb0; *(LAS u32x4*)(lds + AT_BUF + vofs + 32 * 64) = vb1;
;                 __syncthreads();
;                 if (t + 2 < ntile) { const size_t off = (size_t)(t + 2) * 64 * 1024;
;                     ka0 = *(const u32x4*)(kg + off); ka1 = *(const u32x4*)(kg + off + 32 * 1024); va0 = *(const u32x4*)(vg + off); va1 = *(const u32x4*)(vg + off + 32 * 1024);
;                     kb0 = *(const u32x4*)(kg + off + 64 * 1024); kb1 = *(const u32x4*)(kg + off + 96 * 1024); vb0 = *(const u32x4*)(vg + off + 64 * 1024); vb1 = *(const u32x4*)(vg + off + 96 * 1024); }
;                 if (t <= my_top) df_tile<LdsProv, false>(L0, comp, qf, 64 * t, 0, lane, mx, ls, o);
.LBB0_266:
	s_cmp_ge_u32 s36, s30
	s_cselect_b64 s[6:7], -1, 0
	s_and_b64 vcc, exec, s[6:7]
	s_waitcnt vmcnt(7)
	ds_write_b128 v214, v[112:115]
	s_waitcnt vmcnt(5)
	ds_write_b128 v214, v[116:119] offset:4608
	ds_write_b128 v215, v[120:123] offset:18432
	s_waitcnt vmcnt(4)
	ds_write_b128 v215, v[124:127] offset:20480
	s_waitcnt vmcnt(3)
	ds_write_b128 v214, v[128:131] offset:34816
	s_waitcnt vmcnt(2)
	ds_write_b128 v214, v[132:135] offset:39424
	s_waitcnt vmcnt(1)
	ds_write_b128 v215, v[136:139] offset:53248
	s_waitcnt vmcnt(0)
	ds_write_b128 v215, v[140:143] offset:55296
	s_waitcnt lgkmcnt(0)
	s_barrier
	s_cmp_eq_u32 s22, 0
	s_cbranch_scc1 .Ldf_nostag
	s_sleep 6
.Ldf_nostag:
	s_cbranch_vccz .LBB0_269
	s_cmp_gt_u32 s36, s31
	s_cbranch_scc0 .LBB0_270
